# phase 4 dealing change extended to blocks <256 (query tiles 15..12)
# baseline (speedup 1.0000x reference)
; DI void phase_attn2(const Params& p, char* smem) {
;   for (int it = blockIdx.x; it < 1024; it += gridDim.x) {
;     const int j = (it & 511) >> 1;
;     const int idx = (it < 512) ? j : (511 - j);
;     if (it & 1) attn_item<1>(p, idx, smem); else attn_item<3>(p, idx, smem);
;   }
; }
.LBB0_408:
	v_cvt_pk_bf16_f32 v0, v0, v1
	v_cvt_pk_bf16_f32 v1, v2, v3
	global_store_dwordx2 v[16:17], v[0:1], off offset:64
	v_cvt_pk_bf16_f32 v0, v4, v5
	v_cvt_pk_bf16_f32 v1, v6, v7
	global_store_dwordx2 v[16:17], v[0:1], off offset:80
	v_cvt_pk_bf16_f32 v0, v8, v9
	v_cvt_pk_bf16_f32 v1, v10, v11
	global_store_dwordx2 v[16:17], v[0:1], off offset:96
	v_cvt_pk_bf16_f32 v0, v12, v13
	v_cvt_pk_bf16_f32 v1, v14, v15
	v_readlane_b32 s2, v254, 38
	global_store_dwordx2 v[16:17], v[0:1], off offset:112
	v_readlane_b32 s3, v254, 39
	s_load_dword s2, s[2:3], 0x0
	s_waitcnt lgkmcnt(0)
	s_add_i32 s93, s2, s93
	s_and_b32 s2, s93, 0x1ff
	s_cmpk_gt_i32 s93, 0x3ff
	s_cbranch_scc1 .Lp4_tail
	s_cmpk_lt_u32 s2, 0x100
	s_cbranch_scc0 .LBB0_409
	s_bitcmp0_b32 s2, 0
	s_cbranch_scc1 .LBB0_145
	s_branch .LBB0_409
.Lp4_tail:
	s_cmpk_lt_u32 s2, 0x100
	s_cbranch_scc0 .LBB0_145
	s_bitcmp1_b32 s93, 0
	s_cbranch_scc0 .LBB0_145
	s_cmpk_ge_i32 s93, 0x600
	s_cbranch_scc1 .LBB0_145
	s_sub_i32 s93, s93, 0x201
